# cooperative-groups grid.sync after P0 replaced by the xcd two-level barrier
# speedup vs baseline: 1.2106x; 1.0040x over previous
.LBB0_40:
	s_waitcnt vmcnt(0) lgkmcnt(0)
	v_readlane_b32 s0, v253, 16
	v_readlane_b32 s1, v253, 17
	s_waitcnt vmcnt(0)
	s_andn2_b64 vcc, exec, s[0:1]
	s_waitcnt vmcnt(0)
	v_cndmask_b32_e64 v0, 0, 1, s[0:1]
	v_cmp_ne_u32_e64 s[4:5], 1, v0
	s_barrier
	s_nop 0
	v_writelane_b32 v253, s4, 39
	s_nop 1
	v_writelane_b32 v253, s5, 40
	s_cbranch_vccnz .Lxb0_174
	v_mov_b32_e32 v0, v174
	s_nop 0
	v_cmp_eq_u32_e32 vcc, 0, v0
	s_and_saveexec_b64 s[0:1], vcc
	s_cbranch_execz .Lxb0_173
	s_add_i32 s4, 0, 0x23fc0
	v_mov_b32_e32 v0, s4
	s_waitcnt vmcnt(0) expcnt(0) lgkmcnt(0)
	ds_read_b32 v2, v0
	s_add_i32 s4, 0, 0x23fc4
	v_mov_b32_e32 v0, s4
	ds_read_b32 v0, v0
	s_waitcnt lgkmcnt(1)
	v_cmp_ne_u32_e32 vcc, 0, v2
	s_cbranch_vccnz .Lxb0_137
	s_add_u32 s4, s66, 0x1300200
	s_addc_u32 s5, s67, 0
	s_add_u32 s6, s66, 0x1300400
	s_addc_u32 s7, s67, 0
	s_add_u32 s8, s66, 0x1300500
	s_addc_u32 s9, s67, 0
	s_add_u32 s10, s66, 0x1300600
	s_addc_u32 s11, s67, 0
	s_add_u32 s12, s66, 0x1300700
	s_addc_u32 s13, s67, 0
	s_add_u32 s14, s66, 0x1300800
	s_addc_u32 s15, s67, 0
	s_add_u32 s16, s66, 0x1300900
	s_addc_u32 s17, s67, 0
	s_add_u32 s18, s66, 0x1300a00
	s_addc_u32 s19, s67, 0
	s_add_u32 s20, s66, 0x1300b00
	s_addc_u32 s21, s67, 0
	s_add_u32 s22, s66, 0x1300c00
	s_addc_u32 s23, s67, 0
	s_add_u32 s24, s66, 0x1300d00
	s_addc_u32 s25, s67, 0
	s_add_u32 s26, s66, 0x1300e00
	s_addc_u32 s27, s67, 0
	s_add_u32 s28, s66, 0x1300f00
	s_addc_u32 s29, s67, 0
	s_add_u32 s30, s66, 0x1301000
	s_addc_u32 s31, s67, 0
	s_add_u32 s34, s66, 0x1301100
	s_addc_u32 s35, s67, 0
	s_add_u32 s36, s66, 0x1301200
	s_addc_u32 s37, s67, 0
	s_mul_i32 s46, s95, s85
	s_add_u32 s38, s66, 0x1301300
	s_mul_i32 s46, s46, s94
	s_addc_u32 s39, s67, 0
	s_mov_b32 s47, 1
	v_mov_b32_e32 v16, 0
	s_branch .Lxb0_125

.Lxb0_174:
	s_add_u32 s12, s66, 0xb00000
	s_addc_u32 s13, s67, 0
	s_cmpk_lt_i32 s87, 0x900
	v_mov_b32_e32 v0, v174
	v_mov_b32_e32 v8, v174
	s_cselect_b64 s[0:1], -1, 0
	s_cmpk_gt_i32 s87, 0x8ff
	s_barrier
	s_cbranch_scc1 .LBB0_52
	s_ashr_i32 s2, s87, 31
	s_lshr_b32 s2, s2, 29
	s_add_i32 s2, s87, s2
	s_and_b32 s3, s2, -8
	s_sub_i32 s3, s87, s3
	s_cmp_lt_i32 s3, 0
	s_movk_i32 s4, 0x121
	s_cselect_b32 s4, s4, 0x120
	s_mul_i32 s3, s3, s4
	s_ashr_i32 s2, s2, 3
	s_add_i32 s3, s3, s2
	s_mul_hi_i32 s2, s3, 0x2aaaaaab
	s_lshr_b32 s4, s2, 31
	s_ashr_i32 s2, s2, 4
	s_add_i32 s2, s2, s4
	s_lshl_b32 s4, s2, 3
	s_mulk_i32 s2, 0x60
	s_sub_i32 s2, s3, s2
	s_bfe_i32 s3, s2, 0x80000
	s_bfe_u32 s3, s3, 0x3000c
	s_add_i32 s3, s2, s3
	s_bfe_i32 s5, s3, 0x80000
	s_and_b32 s3, s3, 0xf8
	s_sub_i32 s2, s2, s3
	s_sext_i32_i16 s5, s5
	s_sext_i32_i8 s2, s2
	s_add_i32 s26, s4, s2
	s_ashr_i32 s28, s5, 3
